# phases 1 and 10: accumulators no longer zeroed at the tile header; in the first K iteration the first MFMA per accumulator takes C = 0 (out-of-line copies of the phase 1-4 MFMA blocks); on v076
# speedup vs baseline: 1.0050x; 1.0029x over previous
.LBB0_177:
	s_ashr_i32 s45, s44, 31
	v_cmp_lt_i64_e32 vcc, s[46:47], v[144:145]
	s_lshl_b64 s[46:47], s[44:45], 19
	s_add_u32 s46, s68, s46
	s_addc_u32 s47, s69, s47
	s_and_b64 s[48:49], vcc, exec
	s_cselect_b32 s11, s47, s51
	s_cselect_b32 s13, s46, s50
	s_ashr_i32 s43, s42, 31
	s_lshl_b64 s[48:49], s[42:43], 19
	s_add_u32 s48, s26, s48
	s_addc_u32 s49, s27, s49
	s_and_b64 s[54:55], vcc, exec
	s_cselect_b32 s17, s49, s53
	s_cselect_b32 s43, s48, s52
	s_add_u32 s50, s50, 0x40080
	s_addc_u32 s51, s51, 0
	s_add_u32 s45, s52, 0x100
	s_addc_u32 s91, s53, 0
	s_mov_b32 s92, -2
	s_waitcnt lgkmcnt(0)
.LBB0_178:
	ds_read_b128 v[148:151], v159
	ds_read_b128 v[152:155], v159 offset:1024
	ds_read_b128 v[164:167], v159 offset:2048
	ds_read_b128 v[168:171], v159 offset:3072
	s_add_u32 s52, s50, 0xfffc0080
	s_addc_u32 s53, s51, -1
	s_cmp_eq_u32 s92, 12
	s_cselect_b32 s55, s11, s53
	s_cselect_b32 s54, s13, s52
	s_cselect_b32 s53, s17, s91
	s_cselect_b32 s52, s43, s45
	v_lshl_add_u64 v[156:157], s[50:51], 0, v[140:141]
	s_add_i32 m0, s58, 0xc000
	ds_read_b128 v[172:175], v160
	ds_read_b128 v[176:179], v160 offset:1024
	ds_read_b128 v[180:183], v160 offset:2048
	ds_read_b128 v[184:187], v160 offset:3072
	ds_read_b128 v[188:191], v160 offset:4096
	ds_read_b128 v[196:199], v160 offset:5120
	ds_read_b128 v[200:203], v160 offset:6144
	ds_read_b128 v[204:207], v160 offset:7168
	global_load_lds_dwordx4 v[156:157], off
	v_lshl_add_u64 v[156:157], s[50:51], 0, v[142:143]
	s_add_i32 m0, s58, 0xe000
	s_nop 0
	global_load_lds_dwordx4 v[156:157], off
	s_waitcnt lgkmcnt(8)
	s_barrier
	s_waitcnt lgkmcnt(0)
	s_setprio 1
	s_waitcnt lgkmcnt(0)
	s_cmp_eq_u32 s92, -2
	s_cbranch_scc1 .Lz1_0_first
	v_mfma_f32_16x16x32_bf16 v[124:127], v[148:151], v[172:175], v[124:127]
	v_mfma_f32_16x16x32_bf16 v[120:123], v[164:167], v[172:175], v[120:123]
	v_mfma_f32_16x16x32_bf16 v[108:111], v[148:151], v[180:183], v[108:111]
	v_mfma_f32_16x16x32_bf16 v[104:107], v[164:167], v[180:183], v[104:107]
	v_mfma_f32_16x16x32_bf16 v[92:95], v[148:151], v[188:191], v[92:95]
	v_mfma_f32_16x16x32_bf16 v[88:91], v[164:167], v[188:191], v[88:91]
	v_mfma_f32_16x16x32_bf16 v[76:79], v[148:151], v[200:203], v[76:79]
	v_mfma_f32_16x16x32_bf16 v[72:75], v[164:167], v[200:203], v[72:75]
	v_mfma_f32_16x16x32_bf16 v[124:127], v[152:155], v[176:179], v[124:127]
	v_mfma_f32_16x16x32_bf16 v[120:123], v[168:171], v[176:179], v[120:123]
	v_mfma_f32_16x16x32_bf16 v[108:111], v[152:155], v[184:187], v[108:111]
	v_mfma_f32_16x16x32_bf16 v[104:107], v[168:171], v[184:187], v[104:107]
	v_mfma_f32_16x16x32_bf16 v[92:95], v[152:155], v[196:199], v[92:95]
	v_mfma_f32_16x16x32_bf16 v[88:91], v[168:171], v[196:199], v[88:91]
	v_mfma_f32_16x16x32_bf16 v[76:79], v[152:155], v[204:207], v[76:79]
	v_mfma_f32_16x16x32_bf16 v[72:75], v[168:171], v[204:207], v[72:75]
.Lz1_0_join:
	s_setprio 0
	s_barrier
	s_add_i32 s93, s89, s57
	v_lshl_add_u64 v[156:157], s[52:53], 0, v[130:131]
	s_mov_b32 m0, s93
	ds_read_b128 v[208:211], v161
	ds_read_b128 v[212:215], v161 offset:1024
	ds_read_b128 v[216:219], v161 offset:2048
	ds_read_b128 v[220:223], v161 offset:3072
	global_load_lds_dwordx4 v[156:157], off
	v_lshl_add_u64 v[224:225], s[52:53], 0, v[134:135]
	s_add_i32 m0, s93, 0x2000
	s_nop 0
	global_load_lds_dwordx4 v[224:225], off
	s_barrier
	s_waitcnt lgkmcnt(0)
	s_setprio 1
	s_waitcnt lgkmcnt(0)
	s_cmp_eq_u32 s92, -2
	s_cbranch_scc1 .Lz1_1_first
	v_mfma_f32_16x16x32_bf16 v[116:119], v[208:211], v[172:175], v[116:119]
	v_mfma_f32_16x16x32_bf16 v[112:115], v[216:219], v[172:175], v[112:115]
	v_mfma_f32_16x16x32_bf16 v[100:103], v[208:211], v[180:183], v[100:103]
	v_mfma_f32_16x16x32_bf16 v[96:99], v[216:219], v[180:183], v[96:99]
	v_mfma_f32_16x16x32_bf16 v[84:87], v[208:211], v[188:191], v[84:87]
	v_mfma_f32_16x16x32_bf16 v[80:83], v[216:219], v[188:191], v[80:83]
	v_mfma_f32_16x16x32_bf16 v[68:71], v[208:211], v[200:203], v[68:71]
	v_mfma_f32_16x16x32_bf16 v[64:67], v[216:219], v[200:203], v[64:67]
	v_mfma_f32_16x16x32_bf16 v[116:119], v[212:215], v[176:179], v[116:119]
	v_mfma_f32_16x16x32_bf16 v[112:115], v[220:223], v[176:179], v[112:115]
	v_mfma_f32_16x16x32_bf16 v[100:103], v[212:215], v[184:187], v[100:103]
	v_mfma_f32_16x16x32_bf16 v[96:99], v[220:223], v[184:187], v[96:99]
	v_mfma_f32_16x16x32_bf16 v[84:87], v[212:215], v[196:199], v[84:87]
	v_mfma_f32_16x16x32_bf16 v[80:83], v[220:223], v[196:199], v[80:83]
	v_mfma_f32_16x16x32_bf16 v[68:71], v[212:215], v[204:207], v[68:71]
	v_mfma_f32_16x16x32_bf16 v[64:67], v[220:223], v[204:207], v[64:67]
.Lz1_1_join:
	s_setprio 0
	s_mov_b32 m0, s58
	v_lshl_add_u64 v[226:227], s[54:55], 0, v[128:129]
	s_barrier
	ds_read_b128 v[172:175], v160 offset:16384
	ds_read_b128 v[176:179], v160 offset:17408
	ds_read_b128 v[180:183], v160 offset:18432
	ds_read_b128 v[184:187], v160 offset:19456
	ds_read_b128 v[188:191], v160 offset:20480
	ds_read_b128 v[196:199], v160 offset:21504
	ds_read_b128 v[200:203], v160 offset:22528
	ds_read_b128 v[204:207], v160 offset:23552
	global_load_lds_dwordx4 v[226:227], off
	v_lshl_add_u64 v[228:229], s[54:55], 0, v[132:133]
	s_mov_b32 m0, s59
	s_nop 0
	global_load_lds_dwordx4 v[228:229], off
	s_barrier
	s_waitcnt lgkmcnt(0)
	s_setprio 1
	s_waitcnt lgkmcnt(0)
	s_cmp_eq_u32 s92, -2
	s_cbranch_scc1 .Lz1_2_first
	v_mfma_f32_16x16x32_bf16 v[60:63], v[148:151], v[172:175], v[60:63]
	v_mfma_f32_16x16x32_bf16 v[56:59], v[164:167], v[172:175], v[56:59]
	v_mfma_f32_16x16x32_bf16 v[44:47], v[148:151], v[180:183], v[44:47]
	v_mfma_f32_16x16x32_bf16 v[40:43], v[164:167], v[180:183], v[40:43]
	v_mfma_f32_16x16x32_bf16 v[28:31], v[148:151], v[188:191], v[28:31]
	v_mfma_f32_16x16x32_bf16 v[24:27], v[164:167], v[188:191], v[24:27]
	v_mfma_f32_16x16x32_bf16 v[12:15], v[148:151], v[200:203], v[12:15]
	v_mfma_f32_16x16x32_bf16 v[8:11], v[164:167], v[200:203], v[8:11]
	v_mfma_f32_16x16x32_bf16 v[60:63], v[152:155], v[176:179], v[60:63]
	v_mfma_f32_16x16x32_bf16 v[56:59], v[168:171], v[176:179], v[56:59]
	v_mfma_f32_16x16x32_bf16 v[44:47], v[152:155], v[184:187], v[44:47]
	v_mfma_f32_16x16x32_bf16 v[40:43], v[168:171], v[184:187], v[40:43]
	v_mfma_f32_16x16x32_bf16 v[28:31], v[152:155], v[196:199], v[28:31]
	v_mfma_f32_16x16x32_bf16 v[24:27], v[168:171], v[196:199], v[24:27]
	v_mfma_f32_16x16x32_bf16 v[12:15], v[152:155], v[204:207], v[12:15]
	v_mfma_f32_16x16x32_bf16 v[8:11], v[168:171], v[204:207], v[8:11]
.Lz1_2_join:
	s_setprio 0
	s_barrier
	s_add_u32 s94, s52, 0x10000
	s_addc_u32 s95, s53, 0
	s_add_i32 s93, s90, s57
	v_lshl_add_u64 v[148:149], s[94:95], 0, v[130:131]
	s_mov_b32 m0, s93
	s_nop 0
	global_load_lds_dwordx4 v[148:149], off
	v_lshl_add_u64 v[148:149], s[94:95], 0, v[134:135]
	s_add_i32 m0, s93, 0x2000
	s_nop 0
	global_load_lds_dwordx4 v[148:149], off
	s_cmp_eq_u32 s98, 0
	s_cbranch_scc1 .Lk1_w4n
	s_mov_b32 s98, 0
	s_waitcnt vmcnt(24)
	s_branch .Lk1_w4j

.Lk1_w4j:
	s_barrier
	s_setprio 1
	s_cmp_eq_u32 s92, -2
	s_cbranch_scc1 .Lz1_3_first
	v_mfma_f32_16x16x32_bf16 v[52:55], v[208:211], v[172:175], v[52:55]
	v_mfma_f32_16x16x32_bf16 v[48:51], v[216:219], v[172:175], v[48:51]
	v_mfma_f32_16x16x32_bf16 v[36:39], v[208:211], v[180:183], v[36:39]
	v_mfma_f32_16x16x32_bf16 v[32:35], v[216:219], v[180:183], v[32:35]
	v_mfma_f32_16x16x32_bf16 v[20:23], v[208:211], v[188:191], v[20:23]
	v_mfma_f32_16x16x32_bf16 v[16:19], v[216:219], v[188:191], v[16:19]
	v_mfma_f32_16x16x32_bf16 v[4:7], v[208:211], v[200:203], v[4:7]
	v_mfma_f32_16x16x32_bf16 v[0:3], v[216:219], v[200:203], v[0:3]
	v_mfma_f32_16x16x32_bf16 v[52:55], v[212:215], v[176:179], v[52:55]
	v_mfma_f32_16x16x32_bf16 v[48:51], v[220:223], v[176:179], v[48:51]
	v_mfma_f32_16x16x32_bf16 v[36:39], v[212:215], v[184:187], v[36:39]
	v_mfma_f32_16x16x32_bf16 v[32:35], v[220:223], v[184:187], v[32:35]
	v_mfma_f32_16x16x32_bf16 v[20:23], v[212:215], v[196:199], v[20:23]
	v_mfma_f32_16x16x32_bf16 v[16:19], v[220:223], v[196:199], v[16:19]
	v_mfma_f32_16x16x32_bf16 v[4:7], v[212:215], v[204:207], v[4:7]
	v_mfma_f32_16x16x32_bf16 v[0:3], v[220:223], v[204:207], v[0:3]
.Lz1_3_join:
	s_setprio 0
	s_add_i32 s93, 0, 0x18000
	v_add_u32_e32 v136, s93, v158
	s_barrier
	ds_read_b128 v[148:151], v136
	ds_read_b128 v[152:155], v136 offset:1024
	ds_read_b128 v[164:167], v136 offset:2048
	ds_read_b128 v[168:171], v136 offset:3072
	s_add_u32 s54, s54, 0x40000
	s_addc_u32 s55, s55, 0
	s_mov_b32 m0, s60
	v_lshl_add_u64 v[208:209], s[54:55], 0, v[128:129]
	ds_read_b128 v[172:175], v160 offset:32768
	ds_read_b128 v[176:179], v160 offset:33792
	ds_read_b128 v[180:183], v160 offset:34816
	ds_read_b128 v[184:187], v160 offset:35840
	ds_read_b128 v[188:191], v160 offset:36864
	ds_read_b128 v[196:199], v160 offset:37888
	ds_read_b128 v[200:203], v160 offset:38912
	ds_read_b128 v[204:207], v160 offset:39936
	global_load_lds_dwordx4 v[208:209], off
	v_lshl_add_u64 v[208:209], s[54:55], 0, v[132:133]
	s_mov_b32 m0, s61
	s_nop 0
	global_load_lds_dwordx4 v[208:209], off
	s_waitcnt lgkmcnt(8)
	s_barrier
	s_waitcnt lgkmcnt(0)
	s_setprio 1
	s_waitcnt lgkmcnt(0)
	v_mfma_f32_16x16x32_bf16 v[124:127], v[148:151], v[172:175], v[124:127]
	v_mfma_f32_16x16x32_bf16 v[120:123], v[164:167], v[172:175], v[120:123]
	v_mfma_f32_16x16x32_bf16 v[108:111], v[148:151], v[180:183], v[108:111]
	v_mfma_f32_16x16x32_bf16 v[104:107], v[164:167], v[180:183], v[104:107]
	v_mfma_f32_16x16x32_bf16 v[92:95], v[148:151], v[188:191], v[92:95]
	v_mfma_f32_16x16x32_bf16 v[88:91], v[164:167], v[188:191], v[88:91]
	v_mfma_f32_16x16x32_bf16 v[76:79], v[148:151], v[200:203], v[76:79]
	v_mfma_f32_16x16x32_bf16 v[72:75], v[164:167], v[200:203], v[72:75]
	v_mfma_f32_16x16x32_bf16 v[124:127], v[152:155], v[176:179], v[124:127]
	v_mfma_f32_16x16x32_bf16 v[120:123], v[168:171], v[176:179], v[120:123]
	v_mfma_f32_16x16x32_bf16 v[108:111], v[152:155], v[184:187], v[108:111]
	v_mfma_f32_16x16x32_bf16 v[104:107], v[168:171], v[184:187], v[104:107]
	v_mfma_f32_16x16x32_bf16 v[92:95], v[152:155], v[196:199], v[92:95]
	v_mfma_f32_16x16x32_bf16 v[88:91], v[168:171], v[196:199], v[88:91]
	v_mfma_f32_16x16x32_bf16 v[76:79], v[152:155], v[204:207], v[76:79]
	v_mfma_f32_16x16x32_bf16 v[72:75], v[168:171], v[204:207], v[72:75]
	s_setprio 0
	s_barrier
	s_add_i32 s54, 0, 0x1c000
	s_add_i32 s55, s93, s57
	v_add_u32_e32 v136, s54, v158
	v_lshl_add_u64 v[156:157], v[156:157], 0, s[0:1]
	s_mov_b32 m0, s55
	ds_read_b128 v[208:211], v136
	ds_read_b128 v[212:215], v136 offset:1024
	ds_read_b128 v[216:219], v136 offset:2048
	ds_read_b128 v[220:223], v136 offset:3072
	global_load_lds_dwordx4 v[156:157], off
	v_lshl_add_u64 v[156:157], v[224:225], 0, s[0:1]
	s_add_i32 m0, s55, 0x2000
	s_nop 0
	global_load_lds_dwordx4 v[156:157], off
	s_barrier
	s_waitcnt lgkmcnt(0)
	s_setprio 1
	s_waitcnt lgkmcnt(0)
	v_mfma_f32_16x16x32_bf16 v[116:119], v[208:211], v[172:175], v[116:119]
	v_mfma_f32_16x16x32_bf16 v[112:115], v[216:219], v[172:175], v[112:115]
	v_mfma_f32_16x16x32_bf16 v[100:103], v[208:211], v[180:183], v[100:103]
	v_mfma_f32_16x16x32_bf16 v[96:99], v[216:219], v[180:183], v[96:99]
	v_mfma_f32_16x16x32_bf16 v[84:87], v[208:211], v[188:191], v[84:87]
	v_mfma_f32_16x16x32_bf16 v[80:83], v[216:219], v[188:191], v[80:83]
	v_mfma_f32_16x16x32_bf16 v[68:71], v[208:211], v[200:203], v[68:71]
	v_mfma_f32_16x16x32_bf16 v[64:67], v[216:219], v[200:203], v[64:67]
	v_mfma_f32_16x16x32_bf16 v[116:119], v[212:215], v[176:179], v[116:119]
	v_mfma_f32_16x16x32_bf16 v[112:115], v[220:223], v[176:179], v[112:115]
	v_mfma_f32_16x16x32_bf16 v[100:103], v[212:215], v[184:187], v[100:103]
	v_mfma_f32_16x16x32_bf16 v[96:99], v[220:223], v[184:187], v[96:99]
	v_mfma_f32_16x16x32_bf16 v[84:87], v[212:215], v[196:199], v[84:87]
	v_mfma_f32_16x16x32_bf16 v[80:83], v[220:223], v[196:199], v[80:83]
	v_mfma_f32_16x16x32_bf16 v[68:71], v[212:215], v[204:207], v[68:71]
	v_mfma_f32_16x16x32_bf16 v[64:67], v[220:223], v[204:207], v[64:67]
	s_setprio 0
	s_mov_b32 m0, s65
	v_lshl_add_u64 v[156:157], v[226:227], 0, s[0:1]
	s_waitcnt vmcnt(10)
	s_barrier
	ds_read_b128 v[172:175], v160 offset:49152
	ds_read_b128 v[176:179], v160 offset:50176
	ds_read_b128 v[180:183], v160 offset:51200
	ds_read_b128 v[184:187], v160 offset:52224
	ds_read_b128 v[188:191], v160 offset:53248
	ds_read_b128 v[196:199], v160 offset:54272
	ds_read_b128 v[200:203], v160 offset:55296
	ds_read_b128 v[204:207], v160 offset:56320
	global_load_lds_dwordx4 v[156:157], off
	v_lshl_add_u64 v[156:157], v[228:229], 0, s[0:1]
	s_mov_b32 m0, s66
	s_nop 0
	global_load_lds_dwordx4 v[156:157], off
	s_barrier
	s_waitcnt lgkmcnt(0)
	s_setprio 1
	s_waitcnt lgkmcnt(0)
	v_mfma_f32_16x16x32_bf16 v[60:63], v[148:151], v[172:175], v[60:63]
	v_mfma_f32_16x16x32_bf16 v[56:59], v[164:167], v[172:175], v[56:59]
	v_mfma_f32_16x16x32_bf16 v[44:47], v[148:151], v[180:183], v[44:47]
	v_mfma_f32_16x16x32_bf16 v[40:43], v[164:167], v[180:183], v[40:43]
	v_mfma_f32_16x16x32_bf16 v[28:31], v[148:151], v[188:191], v[28:31]
	v_mfma_f32_16x16x32_bf16 v[24:27], v[164:167], v[188:191], v[24:27]
	v_mfma_f32_16x16x32_bf16 v[12:15], v[148:151], v[200:203], v[12:15]
	v_mfma_f32_16x16x32_bf16 v[8:11], v[164:167], v[200:203], v[8:11]
	v_mfma_f32_16x16x32_bf16 v[60:63], v[152:155], v[176:179], v[60:63]
	v_mfma_f32_16x16x32_bf16 v[56:59], v[168:171], v[176:179], v[56:59]
	v_mfma_f32_16x16x32_bf16 v[44:47], v[152:155], v[184:187], v[44:47]
	v_mfma_f32_16x16x32_bf16 v[40:43], v[168:171], v[184:187], v[40:43]
	v_mfma_f32_16x16x32_bf16 v[28:31], v[152:155], v[196:199], v[28:31]
	v_mfma_f32_16x16x32_bf16 v[24:27], v[168:171], v[196:199], v[24:27]
	v_mfma_f32_16x16x32_bf16 v[12:15], v[152:155], v[204:207], v[12:15]
	v_mfma_f32_16x16x32_bf16 v[8:11], v[168:171], v[204:207], v[8:11]
	s_setprio 0
	s_barrier
	s_add_u32 s52, s52, 0x10080
	s_addc_u32 s53, s53, 0
	s_add_i32 s54, s54, s57
	v_lshl_add_u64 v[148:149], s[52:53], 0, v[130:131]
	s_mov_b32 m0, s54
	s_nop 0
	global_load_lds_dwordx4 v[148:149], off
	v_lshl_add_u64 v[148:149], s[52:53], 0, v[134:135]
	s_add_i32 m0, s54, 0x2000
	s_nop 0
	global_load_lds_dwordx4 v[148:149], off
	s_waitcnt vmcnt(6)
	s_barrier
	s_setprio 1
	v_mfma_f32_16x16x32_bf16 v[52:55], v[208:211], v[172:175], v[52:55]
	v_mfma_f32_16x16x32_bf16 v[48:51], v[216:219], v[172:175], v[48:51]
	v_mfma_f32_16x16x32_bf16 v[36:39], v[208:211], v[180:183], v[36:39]
	v_mfma_f32_16x16x32_bf16 v[32:35], v[216:219], v[180:183], v[32:35]
	v_mfma_f32_16x16x32_bf16 v[20:23], v[208:211], v[188:191], v[20:23]
	v_mfma_f32_16x16x32_bf16 v[16:19], v[216:219], v[188:191], v[16:19]
	v_mfma_f32_16x16x32_bf16 v[4:7], v[208:211], v[200:203], v[4:7]
	v_mfma_f32_16x16x32_bf16 v[0:3], v[216:219], v[200:203], v[0:3]
	v_mfma_f32_16x16x32_bf16 v[52:55], v[212:215], v[176:179], v[52:55]
	v_mfma_f32_16x16x32_bf16 v[48:51], v[220:223], v[176:179], v[48:51]
	v_mfma_f32_16x16x32_bf16 v[36:39], v[212:215], v[184:187], v[36:39]
	v_mfma_f32_16x16x32_bf16 v[32:35], v[220:223], v[184:187], v[32:35]
	v_mfma_f32_16x16x32_bf16 v[20:23], v[212:215], v[196:199], v[20:23]
	v_mfma_f32_16x16x32_bf16 v[16:19], v[220:223], v[196:199], v[16:19]
	v_mfma_f32_16x16x32_bf16 v[4:7], v[212:215], v[204:207], v[4:7]
	v_mfma_f32_16x16x32_bf16 v[0:3], v[220:223], v[204:207], v[0:3]
	s_setprio 0
	s_add_i32 s92, s92, 2
	s_add_u32 s50, s50, 0x100
	s_addc_u32 s51, s51, 0
	s_add_u32 s45, s45, 0x100
	s_addc_u32 s91, s91, 0
	s_cmp_gt_u32 s92, 13
	s_barrier
	s_cbranch_scc0 .LBB0_178
	s_branch .Lz1_skip
.Lz1_0_first:
	v_mfma_f32_16x16x32_bf16 v[124:127], v[148:151], v[172:175], 0
	v_mfma_f32_16x16x32_bf16 v[120:123], v[164:167], v[172:175], 0
	v_mfma_f32_16x16x32_bf16 v[108:111], v[148:151], v[180:183], 0
	v_mfma_f32_16x16x32_bf16 v[104:107], v[164:167], v[180:183], 0
	v_mfma_f32_16x16x32_bf16 v[92:95], v[148:151], v[188:191], 0
	v_mfma_f32_16x16x32_bf16 v[88:91], v[164:167], v[188:191], 0
	v_mfma_f32_16x16x32_bf16 v[76:79], v[148:151], v[200:203], 0
	v_mfma_f32_16x16x32_bf16 v[72:75], v[164:167], v[200:203], 0
	v_mfma_f32_16x16x32_bf16 v[124:127], v[152:155], v[176:179], v[124:127]
	v_mfma_f32_16x16x32_bf16 v[120:123], v[168:171], v[176:179], v[120:123]
	v_mfma_f32_16x16x32_bf16 v[108:111], v[152:155], v[184:187], v[108:111]
	v_mfma_f32_16x16x32_bf16 v[104:107], v[168:171], v[184:187], v[104:107]
	v_mfma_f32_16x16x32_bf16 v[92:95], v[152:155], v[196:199], v[92:95]
	v_mfma_f32_16x16x32_bf16 v[88:91], v[168:171], v[196:199], v[88:91]
	v_mfma_f32_16x16x32_bf16 v[76:79], v[152:155], v[204:207], v[76:79]
	v_mfma_f32_16x16x32_bf16 v[72:75], v[168:171], v[204:207], v[72:75]
	s_branch .Lz1_0_join
.Lz1_1_first:
	v_mfma_f32_16x16x32_bf16 v[116:119], v[208:211], v[172:175], 0
	v_mfma_f32_16x16x32_bf16 v[112:115], v[216:219], v[172:175], 0
	v_mfma_f32_16x16x32_bf16 v[100:103], v[208:211], v[180:183], 0
	v_mfma_f32_16x16x32_bf16 v[96:99], v[216:219], v[180:183], 0
	v_mfma_f32_16x16x32_bf16 v[84:87], v[208:211], v[188:191], 0
	v_mfma_f32_16x16x32_bf16 v[80:83], v[216:219], v[188:191], 0
	v_mfma_f32_16x16x32_bf16 v[68:71], v[208:211], v[200:203], 0
	v_mfma_f32_16x16x32_bf16 v[64:67], v[216:219], v[200:203], 0
	v_mfma_f32_16x16x32_bf16 v[116:119], v[212:215], v[176:179], v[116:119]
	v_mfma_f32_16x16x32_bf16 v[112:115], v[220:223], v[176:179], v[112:115]
	v_mfma_f32_16x16x32_bf16 v[100:103], v[212:215], v[184:187], v[100:103]
	v_mfma_f32_16x16x32_bf16 v[96:99], v[220:223], v[184:187], v[96:99]
	v_mfma_f32_16x16x32_bf16 v[84:87], v[212:215], v[196:199], v[84:87]
	v_mfma_f32_16x16x32_bf16 v[80:83], v[220:223], v[196:199], v[80:83]
	v_mfma_f32_16x16x32_bf16 v[68:71], v[212:215], v[204:207], v[68:71]
	v_mfma_f32_16x16x32_bf16 v[64:67], v[220:223], v[204:207], v[64:67]
	s_branch .Lz1_1_join
.Lz1_2_first:
	v_mfma_f32_16x16x32_bf16 v[60:63], v[148:151], v[172:175], 0
	v_mfma_f32_16x16x32_bf16 v[56:59], v[164:167], v[172:175], 0
	v_mfma_f32_16x16x32_bf16 v[44:47], v[148:151], v[180:183], 0
	v_mfma_f32_16x16x32_bf16 v[40:43], v[164:167], v[180:183], 0
	v_mfma_f32_16x16x32_bf16 v[28:31], v[148:151], v[188:191], 0
	v_mfma_f32_16x16x32_bf16 v[24:27], v[164:167], v[188:191], 0
	v_mfma_f32_16x16x32_bf16 v[12:15], v[148:151], v[200:203], 0
	v_mfma_f32_16x16x32_bf16 v[8:11], v[164:167], v[200:203], 0
	v_mfma_f32_16x16x32_bf16 v[60:63], v[152:155], v[176:179], v[60:63]
	v_mfma_f32_16x16x32_bf16 v[56:59], v[168:171], v[176:179], v[56:59]
	v_mfma_f32_16x16x32_bf16 v[44:47], v[152:155], v[184:187], v[44:47]
	v_mfma_f32_16x16x32_bf16 v[40:43], v[168:171], v[184:187], v[40:43]
	v_mfma_f32_16x16x32_bf16 v[28:31], v[152:155], v[196:199], v[28:31]
	v_mfma_f32_16x16x32_bf16 v[24:27], v[168:171], v[196:199], v[24:27]
	v_mfma_f32_16x16x32_bf16 v[12:15], v[152:155], v[204:207], v[12:15]
	v_mfma_f32_16x16x32_bf16 v[8:11], v[168:171], v[204:207], v[8:11]
	s_branch .Lz1_2_join
.Lz1_3_first:
	v_mfma_f32_16x16x32_bf16 v[52:55], v[208:211], v[172:175], 0
	v_mfma_f32_16x16x32_bf16 v[48:51], v[216:219], v[172:175], 0
	v_mfma_f32_16x16x32_bf16 v[36:39], v[208:211], v[180:183], 0
	v_mfma_f32_16x16x32_bf16 v[32:35], v[216:219], v[180:183], 0
	v_mfma_f32_16x16x32_bf16 v[20:23], v[208:211], v[188:191], 0
	v_mfma_f32_16x16x32_bf16 v[16:19], v[216:219], v[188:191], 0
	v_mfma_f32_16x16x32_bf16 v[4:7], v[208:211], v[200:203], 0
	v_mfma_f32_16x16x32_bf16 v[0:3], v[216:219], v[200:203], 0
	v_mfma_f32_16x16x32_bf16 v[52:55], v[212:215], v[176:179], v[52:55]
	v_mfma_f32_16x16x32_bf16 v[48:51], v[220:223], v[176:179], v[48:51]
	v_mfma_f32_16x16x32_bf16 v[36:39], v[212:215], v[184:187], v[36:39]
	v_mfma_f32_16x16x32_bf16 v[32:35], v[220:223], v[184:187], v[32:35]
	v_mfma_f32_16x16x32_bf16 v[20:23], v[212:215], v[196:199], v[20:23]
	v_mfma_f32_16x16x32_bf16 v[16:19], v[220:223], v[196:199], v[16:19]
	v_mfma_f32_16x16x32_bf16 v[4:7], v[212:215], v[204:207], v[4:7]
	v_mfma_f32_16x16x32_bf16 v[0:3], v[220:223], v[204:207], v[0:3]
	s_branch .Lz1_3_join
.Lz1_skip:
	v_lshl_add_u32 v148, s12, 8, v139
	v_and_b32_e32 v149, 24, v138
	s_lshl_b32 s11, s10, 8
	s_or_b32 s11, s11, s87
	s_cmp_gt_i32 s10, 11
	s_cbranch_scc1 .Le1_gates
	s_lshr_b32 s13, s10, 1
	s_lshl_b32 s50, s13, 25
	s_add_u32 s50, s20, s50
	s_addc_u32 s51, s21, 0
	s_bfe_u32 s17, s11, 0x30006
	v_ashrrev_i32_e32 v150, 8, v148
	v_and_or_b32 v150, v150, -8, s17
	v_mov_b32_e32 v151, 0
	v_lshlrev_b64 v[150:151], 18, v[150:151]
	v_lshlrev_b32_e32 v136, 7, v148
	v_and_b32_e32 v136, 0x3ff80, v136
	v_lshl_add_u32 v136, v149, 1, v136
	v_lshl_add_u64 v[150:151], v[150:151], 0, v[136:137]
	v_lshl_add_u64 v[150:151], v[150:151], 0, s[50:51]
	s_movk_i32 s11, 0x800
	s_movk_i32 s17, 0x2800
	s_branch .Le1_addr

.LBB0_1092:
	s_ashr_i32 s37, s36, 31
	v_cmp_lt_i64_e32 vcc, s[0:1], v[142:143]
	s_lshl_b64 s[0:1], s[36:37], 19
	s_add_u32 s38, s68, s0
	s_addc_u32 s39, s69, s1
	s_and_b64 s[0:1], vcc, exec
	s_cselect_b32 s37, s39, s45
	s_cselect_b32 s60, s38, s44
	s_ashr_i32 s13, s12, 31
	s_lshl_b64 s[0:1], s[12:13], 19
	s_add_u32 s40, s70, s0
	s_addc_u32 s41, s71, s1
	s_and_b64 s[0:1], vcc, exec
	s_cselect_b32 s13, s41, s43
	s_cselect_b32 s61, s40, s42
	s_add_u32 s0, s44, 0x40080
	s_addc_u32 s1, s45, 0
	s_add_u32 s62, s42, 0x100
	s_addc_u32 s63, s43, 0
	s_mov_b32 s64, -2
.LBB0_1093:
	ds_read_b128 v[146:149], v167
	ds_read_b128 v[150:153], v167 offset:1024
	ds_read_b128 v[178:181], v167 offset:2048
	ds_read_b128 v[182:185], v167 offset:3072
	s_add_u32 s28, s0, 0xfffc0080
	s_addc_u32 s29, s1, -1
	s_cmp_eq_u32 s64, 12
	s_cselect_b32 s45, s37, s29
	s_cselect_b32 s44, s60, s28
	s_cselect_b32 s43, s13, s63
	s_cselect_b32 s42, s61, s62
	v_lshl_add_u64 v[156:157], s[0:1], 0, v[138:139]
	s_add_i32 m0, s47, 0xc000
	ds_read_b128 v[186:189], v171
	ds_read_b128 v[196:199], v171 offset:1024
	ds_read_b128 v[200:203], v171 offset:2048
	ds_read_b128 v[204:207], v171 offset:3072
	ds_read_b128 v[208:211], v171 offset:4096
	ds_read_b128 v[212:215], v171 offset:5120
	ds_read_b128 v[216:219], v171 offset:6144
	ds_read_b128 v[220:223], v171 offset:7168
	global_load_lds_dwordx4 v[156:157], off
	v_lshl_add_u64 v[156:157], s[0:1], 0, v[140:141]
	s_add_i32 m0, s47, 0xe000
	s_nop 0
	global_load_lds_dwordx4 v[156:157], off
	s_waitcnt lgkmcnt(8)
	s_barrier
	s_waitcnt lgkmcnt(0)
	s_setprio 1
	s_waitcnt lgkmcnt(0)
	s_cmp_eq_u32 s64, -2
	s_cbranch_scc1 .Lz10_0_first
	v_mfma_f32_16x16x32_bf16 v[124:127], v[146:149], v[186:189], v[124:127]
	v_mfma_f32_16x16x32_bf16 v[120:123], v[178:181], v[186:189], v[120:123]
	v_mfma_f32_16x16x32_bf16 v[108:111], v[146:149], v[200:203], v[108:111]
	v_mfma_f32_16x16x32_bf16 v[104:107], v[178:181], v[200:203], v[104:107]
	v_mfma_f32_16x16x32_bf16 v[92:95], v[146:149], v[208:211], v[92:95]
	v_mfma_f32_16x16x32_bf16 v[88:91], v[178:181], v[208:211], v[88:91]
	v_mfma_f32_16x16x32_bf16 v[76:79], v[146:149], v[216:219], v[76:79]
	v_mfma_f32_16x16x32_bf16 v[72:75], v[178:181], v[216:219], v[72:75]
	v_mfma_f32_16x16x32_bf16 v[124:127], v[150:153], v[196:199], v[124:127]
	v_mfma_f32_16x16x32_bf16 v[120:123], v[182:185], v[196:199], v[120:123]
	v_mfma_f32_16x16x32_bf16 v[108:111], v[150:153], v[204:207], v[108:111]
	v_mfma_f32_16x16x32_bf16 v[104:107], v[182:185], v[204:207], v[104:107]
	v_mfma_f32_16x16x32_bf16 v[92:95], v[150:153], v[212:215], v[92:95]
	v_mfma_f32_16x16x32_bf16 v[88:91], v[182:185], v[212:215], v[88:91]
	v_mfma_f32_16x16x32_bf16 v[76:79], v[150:153], v[220:223], v[76:79]
	v_mfma_f32_16x16x32_bf16 v[72:75], v[182:185], v[220:223], v[72:75]
.Lz10_0_join:
	s_setprio 0
	s_barrier
	s_add_i32 s28, s56, s11
	v_lshl_add_u64 v[156:157], s[42:43], 0, v[132:133]
	s_mov_b32 m0, s28
	ds_read_b128 v[224:227], v175
	ds_read_b128 v[228:231], v175 offset:1024
	ds_read_b128 v[232:235], v175 offset:2048
	ds_read_b128 v[236:239], v175 offset:3072
	global_load_lds_dwordx4 v[156:157], off
	v_lshl_add_u64 v[160:161], s[42:43], 0, v[128:129]
	s_add_i32 m0, s28, 0x2000
	s_nop 0
	global_load_lds_dwordx4 v[160:161], off
	s_barrier
	s_waitcnt lgkmcnt(0)
	s_setprio 1
	s_waitcnt lgkmcnt(0)
	s_cmp_eq_u32 s64, -2
	s_cbranch_scc1 .Lz10_1_first
	v_mfma_f32_16x16x32_bf16 v[116:119], v[224:227], v[186:189], v[116:119]
	v_mfma_f32_16x16x32_bf16 v[112:115], v[232:235], v[186:189], v[112:115]
	v_mfma_f32_16x16x32_bf16 v[100:103], v[224:227], v[200:203], v[100:103]
	v_mfma_f32_16x16x32_bf16 v[96:99], v[232:235], v[200:203], v[96:99]
	v_mfma_f32_16x16x32_bf16 v[84:87], v[224:227], v[208:211], v[84:87]
	v_mfma_f32_16x16x32_bf16 v[80:83], v[232:235], v[208:211], v[80:83]
	v_mfma_f32_16x16x32_bf16 v[68:71], v[224:227], v[216:219], v[68:71]
	v_mfma_f32_16x16x32_bf16 v[64:67], v[232:235], v[216:219], v[64:67]
	v_mfma_f32_16x16x32_bf16 v[116:119], v[228:231], v[196:199], v[116:119]
	v_mfma_f32_16x16x32_bf16 v[112:115], v[236:239], v[196:199], v[112:115]
	v_mfma_f32_16x16x32_bf16 v[100:103], v[228:231], v[204:207], v[100:103]
	v_mfma_f32_16x16x32_bf16 v[96:99], v[236:239], v[204:207], v[96:99]
	v_mfma_f32_16x16x32_bf16 v[84:87], v[228:231], v[212:215], v[84:87]
	v_mfma_f32_16x16x32_bf16 v[80:83], v[236:239], v[212:215], v[80:83]
	v_mfma_f32_16x16x32_bf16 v[68:71], v[228:231], v[220:223], v[68:71]
	v_mfma_f32_16x16x32_bf16 v[64:67], v[236:239], v[220:223], v[64:67]
.Lz10_1_join:
	s_setprio 0
	s_mov_b32 m0, s47
	v_lshl_add_u64 v[164:165], s[44:45], 0, v[134:135]
	s_barrier
	ds_read_b128 v[186:189], v171 offset:16384
	ds_read_b128 v[196:199], v171 offset:17408
	ds_read_b128 v[200:203], v171 offset:18432
	ds_read_b128 v[204:207], v171 offset:19456
	ds_read_b128 v[208:211], v171 offset:20480
	ds_read_b128 v[212:215], v171 offset:21504
	ds_read_b128 v[216:219], v171 offset:22528
	ds_read_b128 v[220:223], v171 offset:23552
	global_load_lds_dwordx4 v[164:165], off
	v_lshl_add_u64 v[168:169], s[44:45], 0, v[130:131]
	s_mov_b32 m0, s48
	s_nop 0
	global_load_lds_dwordx4 v[168:169], off
	s_barrier
	s_waitcnt lgkmcnt(0)
	s_setprio 1
	s_waitcnt lgkmcnt(0)
	s_cmp_eq_u32 s64, -2
	s_cbranch_scc1 .Lz10_2_first
	v_mfma_f32_16x16x32_bf16 v[60:63], v[146:149], v[186:189], v[60:63]
	v_mfma_f32_16x16x32_bf16 v[56:59], v[178:181], v[186:189], v[56:59]
	v_mfma_f32_16x16x32_bf16 v[44:47], v[146:149], v[200:203], v[44:47]
	v_mfma_f32_16x16x32_bf16 v[40:43], v[178:181], v[200:203], v[40:43]
	v_mfma_f32_16x16x32_bf16 v[28:31], v[146:149], v[208:211], v[28:31]
	v_mfma_f32_16x16x32_bf16 v[24:27], v[178:181], v[208:211], v[24:27]
	v_mfma_f32_16x16x32_bf16 v[12:15], v[146:149], v[216:219], v[12:15]
	v_mfma_f32_16x16x32_bf16 v[8:11], v[178:181], v[216:219], v[8:11]
	v_mfma_f32_16x16x32_bf16 v[60:63], v[150:153], v[196:199], v[60:63]
	v_mfma_f32_16x16x32_bf16 v[56:59], v[182:185], v[196:199], v[56:59]
	v_mfma_f32_16x16x32_bf16 v[44:47], v[150:153], v[204:207], v[44:47]
	v_mfma_f32_16x16x32_bf16 v[40:43], v[182:185], v[204:207], v[40:43]
	v_mfma_f32_16x16x32_bf16 v[28:31], v[150:153], v[212:215], v[28:31]
	v_mfma_f32_16x16x32_bf16 v[24:27], v[182:185], v[212:215], v[24:27]
	v_mfma_f32_16x16x32_bf16 v[12:15], v[150:153], v[220:223], v[12:15]
	v_mfma_f32_16x16x32_bf16 v[8:11], v[182:185], v[220:223], v[8:11]
.Lz10_2_join:
	s_setprio 0
	s_barrier
	s_add_u32 s66, s42, 0x40000
	s_addc_u32 s67, s43, 0
	s_add_i32 s28, s57, s11
	v_lshl_add_u64 v[146:147], s[66:67], 0, v[132:133]
	s_mov_b32 m0, s28
	s_nop 0
	global_load_lds_dwordx4 v[146:147], off
	v_lshl_add_u64 v[146:147], s[66:67], 0, v[128:129]
	s_add_i32 m0, s28, 0x2000
	s_nop 0
	global_load_lds_dwordx4 v[146:147], off
	s_waitcnt vmcnt(6)
	s_barrier
	s_setprio 1
	s_cmp_eq_u32 s64, -2
	s_cbranch_scc1 .Lz10_3_first
	v_mfma_f32_16x16x32_bf16 v[52:55], v[224:227], v[186:189], v[52:55]
	v_mfma_f32_16x16x32_bf16 v[48:51], v[232:235], v[186:189], v[48:51]
	v_mfma_f32_16x16x32_bf16 v[36:39], v[224:227], v[200:203], v[36:39]
	v_mfma_f32_16x16x32_bf16 v[32:35], v[232:235], v[200:203], v[32:35]
	v_mfma_f32_16x16x32_bf16 v[20:23], v[224:227], v[208:211], v[20:23]
	v_mfma_f32_16x16x32_bf16 v[16:19], v[232:235], v[208:211], v[16:19]
	v_mfma_f32_16x16x32_bf16 v[4:7], v[224:227], v[216:219], v[4:7]
	v_mfma_f32_16x16x32_bf16 v[0:3], v[232:235], v[216:219], v[0:3]
	v_mfma_f32_16x16x32_bf16 v[52:55], v[228:231], v[196:199], v[52:55]
	v_mfma_f32_16x16x32_bf16 v[48:51], v[236:239], v[196:199], v[48:51]
	v_mfma_f32_16x16x32_bf16 v[36:39], v[228:231], v[204:207], v[36:39]
	v_mfma_f32_16x16x32_bf16 v[32:35], v[236:239], v[204:207], v[32:35]
	v_mfma_f32_16x16x32_bf16 v[20:23], v[228:231], v[212:215], v[20:23]
	v_mfma_f32_16x16x32_bf16 v[16:19], v[236:239], v[212:215], v[16:19]
	v_mfma_f32_16x16x32_bf16 v[4:7], v[228:231], v[220:223], v[4:7]
	v_mfma_f32_16x16x32_bf16 v[0:3], v[236:239], v[220:223], v[0:3]
.Lz10_3_join:
	s_setprio 0
	s_add_i32 s28, 0, 0x18000
	v_add_u32_e32 v154, s28, v159
	s_barrier
	ds_read_b128 v[146:149], v154
	ds_read_b128 v[150:153], v154 offset:1024
	ds_read_b128 v[178:181], v154 offset:2048
	ds_read_b128 v[182:185], v154 offset:3072
	s_add_u32 s44, s44, 0x40000
	s_addc_u32 s45, s45, 0
	s_mov_b32 m0, s49
	v_lshl_add_u64 v[172:173], s[44:45], 0, v[134:135]
	ds_read_b128 v[186:189], v171 offset:32768
	ds_read_b128 v[196:199], v171 offset:33792
	ds_read_b128 v[200:203], v171 offset:34816
	ds_read_b128 v[204:207], v171 offset:35840
	ds_read_b128 v[208:211], v171 offset:36864
	ds_read_b128 v[212:215], v171 offset:37888
	ds_read_b128 v[216:219], v171 offset:38912
	ds_read_b128 v[220:223], v171 offset:39936
	global_load_lds_dwordx4 v[172:173], off
	v_lshl_add_u64 v[172:173], s[44:45], 0, v[130:131]
	s_mov_b32 m0, s50
	s_nop 0
	global_load_lds_dwordx4 v[172:173], off
	s_waitcnt lgkmcnt(8)
	s_barrier
	s_waitcnt lgkmcnt(0)
	s_setprio 1
	s_waitcnt lgkmcnt(0)
	v_mfma_f32_16x16x32_bf16 v[124:127], v[146:149], v[186:189], v[124:127]
	v_mfma_f32_16x16x32_bf16 v[120:123], v[178:181], v[186:189], v[120:123]
	v_mfma_f32_16x16x32_bf16 v[108:111], v[146:149], v[200:203], v[108:111]
	v_mfma_f32_16x16x32_bf16 v[104:107], v[178:181], v[200:203], v[104:107]
	v_mfma_f32_16x16x32_bf16 v[92:95], v[146:149], v[208:211], v[92:95]
	v_mfma_f32_16x16x32_bf16 v[88:91], v[178:181], v[208:211], v[88:91]
	v_mfma_f32_16x16x32_bf16 v[76:79], v[146:149], v[216:219], v[76:79]
	v_mfma_f32_16x16x32_bf16 v[72:75], v[178:181], v[216:219], v[72:75]
	v_mfma_f32_16x16x32_bf16 v[124:127], v[150:153], v[196:199], v[124:127]
	v_mfma_f32_16x16x32_bf16 v[120:123], v[182:185], v[196:199], v[120:123]
	v_mfma_f32_16x16x32_bf16 v[108:111], v[150:153], v[204:207], v[108:111]
	v_mfma_f32_16x16x32_bf16 v[104:107], v[182:185], v[204:207], v[104:107]
	v_mfma_f32_16x16x32_bf16 v[92:95], v[150:153], v[212:215], v[92:95]
	v_mfma_f32_16x16x32_bf16 v[88:91], v[182:185], v[212:215], v[88:91]
	v_mfma_f32_16x16x32_bf16 v[76:79], v[150:153], v[220:223], v[76:79]
	v_mfma_f32_16x16x32_bf16 v[72:75], v[182:185], v[220:223], v[72:75]
	s_setprio 0
	s_barrier
	s_add_i32 s29, 0, 0x1c000
	s_add_i32 s28, s28, s11
	v_add_u32_e32 v154, s29, v159
	v_lshl_add_u64 v[156:157], v[156:157], 0, s[6:7]
	s_mov_b32 m0, s28
	ds_read_b128 v[224:227], v154
	ds_read_b128 v[228:231], v154 offset:1024
	ds_read_b128 v[232:235], v154 offset:2048
	ds_read_b128 v[236:239], v154 offset:3072
	global_load_lds_dwordx4 v[156:157], off
	v_lshl_add_u64 v[156:157], v[160:161], 0, s[6:7]
	s_add_i32 m0, s28, 0x2000
	s_nop 0
	global_load_lds_dwordx4 v[156:157], off
	s_barrier
	s_waitcnt lgkmcnt(0)
	s_setprio 1
	s_waitcnt lgkmcnt(0)
	v_mfma_f32_16x16x32_bf16 v[116:119], v[224:227], v[186:189], v[116:119]
	v_mfma_f32_16x16x32_bf16 v[112:115], v[232:235], v[186:189], v[112:115]
	v_mfma_f32_16x16x32_bf16 v[100:103], v[224:227], v[200:203], v[100:103]
	v_mfma_f32_16x16x32_bf16 v[96:99], v[232:235], v[200:203], v[96:99]
	v_mfma_f32_16x16x32_bf16 v[84:87], v[224:227], v[208:211], v[84:87]
	v_mfma_f32_16x16x32_bf16 v[80:83], v[232:235], v[208:211], v[80:83]
	v_mfma_f32_16x16x32_bf16 v[68:71], v[224:227], v[216:219], v[68:71]
	v_mfma_f32_16x16x32_bf16 v[64:67], v[232:235], v[216:219], v[64:67]
	v_mfma_f32_16x16x32_bf16 v[116:119], v[228:231], v[196:199], v[116:119]
	v_mfma_f32_16x16x32_bf16 v[112:115], v[236:239], v[196:199], v[112:115]
	v_mfma_f32_16x16x32_bf16 v[100:103], v[228:231], v[204:207], v[100:103]
	v_mfma_f32_16x16x32_bf16 v[96:99], v[236:239], v[204:207], v[96:99]
	v_mfma_f32_16x16x32_bf16 v[84:87], v[228:231], v[212:215], v[84:87]
	v_mfma_f32_16x16x32_bf16 v[80:83], v[236:239], v[212:215], v[80:83]
	v_mfma_f32_16x16x32_bf16 v[68:71], v[228:231], v[220:223], v[68:71]
	v_mfma_f32_16x16x32_bf16 v[64:67], v[236:239], v[220:223], v[64:67]
	s_setprio 0
	s_mov_b32 m0, s53
	v_lshl_add_u64 v[156:157], v[164:165], 0, s[6:7]
	s_barrier
	ds_read_b128 v[186:189], v171 offset:49152
	ds_read_b128 v[196:199], v171 offset:50176
	ds_read_b128 v[200:203], v171 offset:51200
	ds_read_b128 v[204:207], v171 offset:52224
	ds_read_b128 v[208:211], v171 offset:53248
	ds_read_b128 v[212:215], v171 offset:54272
	ds_read_b128 v[216:219], v171 offset:55296
	ds_read_b128 v[220:223], v171 offset:56320
	global_load_lds_dwordx4 v[156:157], off
	v_lshl_add_u64 v[156:157], v[168:169], 0, s[6:7]
	s_mov_b32 m0, s54
	s_nop 0
	global_load_lds_dwordx4 v[156:157], off
	s_barrier
	s_waitcnt lgkmcnt(0)
	s_setprio 1
	s_waitcnt lgkmcnt(0)
	v_mfma_f32_16x16x32_bf16 v[60:63], v[146:149], v[186:189], v[60:63]
	v_mfma_f32_16x16x32_bf16 v[56:59], v[178:181], v[186:189], v[56:59]
	v_mfma_f32_16x16x32_bf16 v[44:47], v[146:149], v[200:203], v[44:47]
	v_mfma_f32_16x16x32_bf16 v[40:43], v[178:181], v[200:203], v[40:43]
	v_mfma_f32_16x16x32_bf16 v[28:31], v[146:149], v[208:211], v[28:31]
	v_mfma_f32_16x16x32_bf16 v[24:27], v[178:181], v[208:211], v[24:27]
	v_mfma_f32_16x16x32_bf16 v[12:15], v[146:149], v[216:219], v[12:15]
	v_mfma_f32_16x16x32_bf16 v[8:11], v[178:181], v[216:219], v[8:11]
	v_mfma_f32_16x16x32_bf16 v[60:63], v[150:153], v[196:199], v[60:63]
	v_mfma_f32_16x16x32_bf16 v[56:59], v[182:185], v[196:199], v[56:59]
	v_mfma_f32_16x16x32_bf16 v[44:47], v[150:153], v[204:207], v[44:47]
	v_mfma_f32_16x16x32_bf16 v[40:43], v[182:185], v[204:207], v[40:43]
	v_mfma_f32_16x16x32_bf16 v[28:31], v[150:153], v[212:215], v[28:31]
	v_mfma_f32_16x16x32_bf16 v[24:27], v[182:185], v[212:215], v[24:27]
	v_mfma_f32_16x16x32_bf16 v[12:15], v[150:153], v[220:223], v[12:15]
	v_mfma_f32_16x16x32_bf16 v[8:11], v[182:185], v[220:223], v[8:11]
	s_setprio 0
	s_barrier
	s_add_u32 s42, s42, 0x40080
	s_addc_u32 s43, s43, 0
	s_add_i32 s28, s29, s11
	v_lshl_add_u64 v[146:147], s[42:43], 0, v[132:133]
	s_mov_b32 m0, s28
	s_nop 0
	global_load_lds_dwordx4 v[146:147], off
	v_lshl_add_u64 v[146:147], s[42:43], 0, v[128:129]
	s_add_i32 m0, s28, 0x2000
	s_nop 0
	global_load_lds_dwordx4 v[146:147], off
	s_waitcnt vmcnt(6)
	s_barrier
	s_setprio 1
	v_mfma_f32_16x16x32_bf16 v[52:55], v[224:227], v[186:189], v[52:55]
	v_mfma_f32_16x16x32_bf16 v[48:51], v[232:235], v[186:189], v[48:51]
	v_mfma_f32_16x16x32_bf16 v[36:39], v[224:227], v[200:203], v[36:39]
	v_mfma_f32_16x16x32_bf16 v[32:35], v[232:235], v[200:203], v[32:35]
	v_mfma_f32_16x16x32_bf16 v[20:23], v[224:227], v[208:211], v[20:23]
	v_mfma_f32_16x16x32_bf16 v[16:19], v[232:235], v[208:211], v[16:19]
	v_mfma_f32_16x16x32_bf16 v[4:7], v[224:227], v[216:219], v[4:7]
	v_mfma_f32_16x16x32_bf16 v[0:3], v[232:235], v[216:219], v[0:3]
	v_mfma_f32_16x16x32_bf16 v[52:55], v[228:231], v[196:199], v[52:55]
	v_mfma_f32_16x16x32_bf16 v[48:51], v[236:239], v[196:199], v[48:51]
	v_mfma_f32_16x16x32_bf16 v[36:39], v[228:231], v[204:207], v[36:39]
	v_mfma_f32_16x16x32_bf16 v[32:35], v[236:239], v[204:207], v[32:35]
	v_mfma_f32_16x16x32_bf16 v[20:23], v[228:231], v[212:215], v[20:23]
	v_mfma_f32_16x16x32_bf16 v[16:19], v[236:239], v[212:215], v[16:19]
	v_mfma_f32_16x16x32_bf16 v[4:7], v[228:231], v[220:223], v[4:7]
	v_mfma_f32_16x16x32_bf16 v[0:3], v[236:239], v[220:223], v[0:3]
	s_setprio 0
	s_add_i32 s64, s64, 2
	s_add_u32 s0, s0, 0x100
	s_addc_u32 s1, s1, 0
	s_add_u32 s62, s62, 0x100
	s_addc_u32 s63, s63, 0
	s_cmp_gt_u32 s64, 13
	s_barrier
	s_cbranch_scc0 .LBB0_1093
	s_branch .Lz10_skip
.Lz10_0_first:
	v_mfma_f32_16x16x32_bf16 v[124:127], v[146:149], v[186:189], 0
	v_mfma_f32_16x16x32_bf16 v[120:123], v[178:181], v[186:189], 0
	v_mfma_f32_16x16x32_bf16 v[108:111], v[146:149], v[200:203], 0
	v_mfma_f32_16x16x32_bf16 v[104:107], v[178:181], v[200:203], 0
	v_mfma_f32_16x16x32_bf16 v[92:95], v[146:149], v[208:211], 0
	v_mfma_f32_16x16x32_bf16 v[88:91], v[178:181], v[208:211], 0
	v_mfma_f32_16x16x32_bf16 v[76:79], v[146:149], v[216:219], 0
	v_mfma_f32_16x16x32_bf16 v[72:75], v[178:181], v[216:219], 0
	v_mfma_f32_16x16x32_bf16 v[124:127], v[150:153], v[196:199], v[124:127]
	v_mfma_f32_16x16x32_bf16 v[120:123], v[182:185], v[196:199], v[120:123]
	v_mfma_f32_16x16x32_bf16 v[108:111], v[150:153], v[204:207], v[108:111]
	v_mfma_f32_16x16x32_bf16 v[104:107], v[182:185], v[204:207], v[104:107]
	v_mfma_f32_16x16x32_bf16 v[92:95], v[150:153], v[212:215], v[92:95]
	v_mfma_f32_16x16x32_bf16 v[88:91], v[182:185], v[212:215], v[88:91]
	v_mfma_f32_16x16x32_bf16 v[76:79], v[150:153], v[220:223], v[76:79]
	v_mfma_f32_16x16x32_bf16 v[72:75], v[182:185], v[220:223], v[72:75]
	s_branch .Lz10_0_join
.Lz10_1_first:
	v_mfma_f32_16x16x32_bf16 v[116:119], v[224:227], v[186:189], 0
	v_mfma_f32_16x16x32_bf16 v[112:115], v[232:235], v[186:189], 0
	v_mfma_f32_16x16x32_bf16 v[100:103], v[224:227], v[200:203], 0
	v_mfma_f32_16x16x32_bf16 v[96:99], v[232:235], v[200:203], 0
	v_mfma_f32_16x16x32_bf16 v[84:87], v[224:227], v[208:211], 0
	v_mfma_f32_16x16x32_bf16 v[80:83], v[232:235], v[208:211], 0
	v_mfma_f32_16x16x32_bf16 v[68:71], v[224:227], v[216:219], 0
	v_mfma_f32_16x16x32_bf16 v[64:67], v[232:235], v[216:219], 0
	v_mfma_f32_16x16x32_bf16 v[116:119], v[228:231], v[196:199], v[116:119]
	v_mfma_f32_16x16x32_bf16 v[112:115], v[236:239], v[196:199], v[112:115]
	v_mfma_f32_16x16x32_bf16 v[100:103], v[228:231], v[204:207], v[100:103]
	v_mfma_f32_16x16x32_bf16 v[96:99], v[236:239], v[204:207], v[96:99]
	v_mfma_f32_16x16x32_bf16 v[84:87], v[228:231], v[212:215], v[84:87]
	v_mfma_f32_16x16x32_bf16 v[80:83], v[236:239], v[212:215], v[80:83]
	v_mfma_f32_16x16x32_bf16 v[68:71], v[228:231], v[220:223], v[68:71]
	v_mfma_f32_16x16x32_bf16 v[64:67], v[236:239], v[220:223], v[64:67]
	s_branch .Lz10_1_join
.Lz10_2_first:
	v_mfma_f32_16x16x32_bf16 v[60:63], v[146:149], v[186:189], 0
	v_mfma_f32_16x16x32_bf16 v[56:59], v[178:181], v[186:189], 0
	v_mfma_f32_16x16x32_bf16 v[44:47], v[146:149], v[200:203], 0
	v_mfma_f32_16x16x32_bf16 v[40:43], v[178:181], v[200:203], 0
	v_mfma_f32_16x16x32_bf16 v[28:31], v[146:149], v[208:211], 0
	v_mfma_f32_16x16x32_bf16 v[24:27], v[178:181], v[208:211], 0
	v_mfma_f32_16x16x32_bf16 v[12:15], v[146:149], v[216:219], 0
	v_mfma_f32_16x16x32_bf16 v[8:11], v[178:181], v[216:219], 0
	v_mfma_f32_16x16x32_bf16 v[60:63], v[150:153], v[196:199], v[60:63]
	v_mfma_f32_16x16x32_bf16 v[56:59], v[182:185], v[196:199], v[56:59]
	v_mfma_f32_16x16x32_bf16 v[44:47], v[150:153], v[204:207], v[44:47]
	v_mfma_f32_16x16x32_bf16 v[40:43], v[182:185], v[204:207], v[40:43]
	v_mfma_f32_16x16x32_bf16 v[28:31], v[150:153], v[212:215], v[28:31]
	v_mfma_f32_16x16x32_bf16 v[24:27], v[182:185], v[212:215], v[24:27]
	v_mfma_f32_16x16x32_bf16 v[12:15], v[150:153], v[220:223], v[12:15]
	v_mfma_f32_16x16x32_bf16 v[8:11], v[182:185], v[220:223], v[8:11]
	s_branch .Lz10_2_join
.Lz10_3_first:
	v_mfma_f32_16x16x32_bf16 v[52:55], v[224:227], v[186:189], 0
	v_mfma_f32_16x16x32_bf16 v[48:51], v[232:235], v[186:189], 0
	v_mfma_f32_16x16x32_bf16 v[36:39], v[224:227], v[200:203], 0
	v_mfma_f32_16x16x32_bf16 v[32:35], v[232:235], v[200:203], 0
	v_mfma_f32_16x16x32_bf16 v[20:23], v[224:227], v[208:211], 0
	v_mfma_f32_16x16x32_bf16 v[16:19], v[232:235], v[208:211], 0
	v_mfma_f32_16x16x32_bf16 v[4:7], v[224:227], v[216:219], 0
	v_mfma_f32_16x16x32_bf16 v[0:3], v[232:235], v[216:219], 0
	v_mfma_f32_16x16x32_bf16 v[52:55], v[228:231], v[196:199], v[52:55]
	v_mfma_f32_16x16x32_bf16 v[48:51], v[236:239], v[196:199], v[48:51]
	v_mfma_f32_16x16x32_bf16 v[36:39], v[228:231], v[204:207], v[36:39]
	v_mfma_f32_16x16x32_bf16 v[32:35], v[236:239], v[204:207], v[32:35]
	v_mfma_f32_16x16x32_bf16 v[20:23], v[228:231], v[212:215], v[20:23]
	v_mfma_f32_16x16x32_bf16 v[16:19], v[236:239], v[212:215], v[16:19]
	v_mfma_f32_16x16x32_bf16 v[4:7], v[228:231], v[220:223], v[4:7]
	v_mfma_f32_16x16x32_bf16 v[0:3], v[236:239], v[220:223], v[0:3]
	s_branch .Lz10_3_join
.Lz10_skip:
	v_lshl_add_u32 v168, s4, 8, v155
	v_or_b32_e32 v164, 16, v168
	v_or_b32_e32 v160, 32, v168
	v_or_b32_e32 v156, 48, v168
	v_add_u32_e32 v152, 0x80, v168
	v_add_u32_e32 v150, 0x90, v168
	v_add_u32_e32 v148, 0xa0, v168
	v_add_u32_e32 v146, 0xb0, v168
	v_lshl_or_b32 v172, s5, 7, v163
	v_mov_b32_e32 v178, v240
	v_mov_b32_e32 v179, v240
	v_mov_b32_e32 v154, v241
	s_and_b32 s0, s36, 0x7f
	v_lshl_add_u32 v228, s0, 8, v155
	v_mov_b32_e32 v229, 0
	v_lshlrev_b32_e32 v228, 6, v228
	v_lshl_add_u64 v[230:231], v[136:137], 0, v[228:229]
	v_mov_b32_e32 v228, 0x2000
	v_lshl_add_u64 v[232:233], v[230:231], 0, v[228:229]
	global_load_dwordx4 v[216:219], v[230:231], off
	global_load_dwordx4 v[220:223], v[230:231], off offset:1024
	global_load_dwordx4 v[224:227], v[230:231], off offset:2048
	global_load_dwordx4 v[196:199], v[230:231], off offset:3072
	global_load_dwordx4 v[200:203], v[232:233], off
	global_load_dwordx4 v[204:207], v[232:233], off offset:1024
	global_load_dwordx4 v[208:211], v[232:233], off offset:2048
	global_load_dwordx4 v[212:215], v[232:233], off offset:3072
	v_pk_mul_f32 v[124:125], v[124:125], v[178:179] op_sel_hi:[1,0]
	v_pk_mul_f32 v[126:127], v[126:127], v[178:179] op_sel_hi:[1,0]
	v_mul_f32_e32 v147, 0xbfb8aa3b, v124
	v_exp_f32_e32 v147, v147
	v_mul_f32_e32 v149, 0xbfb8aa3b, v125
	v_exp_f32_e32 v149, v149
	v_mul_f32_e32 v151, 0xbfb8aa3b, v127
	v_add_f32_e32 v147, 1.0, v147
	v_rcp_f32_e32 v180, v147
	v_add_f32_e32 v147, 1.0, v149
	v_mul_f32_e32 v149, 0xbfb8aa3b, v126
	v_exp_f32_e32 v149, v149
	v_exp_f32_e32 v151, v151
	v_rcp_f32_e32 v181, v147
	v_pk_mul_f32 v[116:117], v[116:117], v[178:179] op_sel_hi:[1,0]
	v_add_f32_e32 v147, 1.0, v149
	v_rcp_f32_e32 v182, v147
	v_add_f32_e32 v147, 1.0, v151
	v_rcp_f32_e32 v183, v147
	v_pk_mul_f32 v[124:125], v[124:125], v[180:181]
	v_pk_mul_f32 v[120:121], v[120:121], v[178:179] op_sel_hi:[1,0]
	v_pk_mul_f32 v[116:117], v[116:117], v[124:125]
	v_pk_mul_f32 v[124:125], v[126:127], v[182:183]
	v_mul_f32_e32 v126, 0xbfb8aa3b, v120
	v_exp_f32_e32 v126, v126
	v_pk_mul_f32 v[118:119], v[118:119], v[178:179] op_sel_hi:[1,0]
	v_pk_mul_f32 v[122:123], v[122:123], v[178:179] op_sel_hi:[1,0]
	v_pk_mul_f32 v[118:119], v[118:119], v[124:125]
	v_mul_f32_e32 v124, 0xbfb8aa3b, v121
	v_exp_f32_e32 v125, v124
	v_add_f32_e32 v124, 1.0, v126
	v_mul_f32_e32 v126, 0xbfb8aa3b, v122
	v_mul_f32_e32 v127, 0xbfb8aa3b, v123
	v_exp_f32_e32 v126, v126
	v_exp_f32_e32 v127, v127
	v_add_f32_e32 v125, 1.0, v125
	v_rcp_f32_e32 v124, v124
	v_rcp_f32_e32 v125, v125
	v_add_f32_e32 v126, 1.0, v126
	v_add_f32_e32 v127, 1.0, v127
	v_rcp_f32_e32 v126, v126
	v_rcp_f32_e32 v127, v127
	v_pk_mul_f32 v[112:113], v[112:113], v[178:179] op_sel_hi:[1,0]
	v_pk_mul_f32 v[120:121], v[120:121], v[124:125]
	v_pk_mul_f32 v[114:115], v[114:115], v[178:179] op_sel_hi:[1,0]
	v_pk_mul_f32 v[112:113], v[112:113], v[120:121]
	v_pk_mul_f32 v[120:121], v[122:123], v[126:127]
	v_ashrrev_i32_e32 v173, 31, v172
	v_pk_mul_f32 v[114:115], v[114:115], v[120:121]
	v_cvt_pk_bf16_f32 v116, v116, v117
	v_cvt_pk_bf16_f32 v117, v118, v119
	v_cvt_pk_bf16_f32 v118, v112, v113
	v_mov_b64_e32 v[112:113], s[20:21]
	v_cvt_pk_bf16_f32 v119, v114, v115
	v_mad_i64_i32 v[120:121], s[0:1], v168, s59, v[112:113]
	v_lshlrev_b64 v[114:115], 1, v[172:173]
	v_lshl_add_u64 v[120:121], v[120:121], 0, v[114:115]
	v_pk_mul_f32 v[108:109], v[108:109], v[176:177] op_sel_hi:[1,0]
	global_store_dwordx4 v[120:121], v[116:119], off
	v_mul_f32_e32 v122, 0xbfb8aa3b, v108
	v_pk_mul_f32 v[110:111], v[110:111], v[176:177] op_sel_hi:[1,0]
	v_mul_f32_e32 v116, 0xbfb8aa3b, v109
	v_exp_f32_e32 v122, v122
	v_exp_f32_e32 v117, v116
	v_mul_f32_e32 v118, 0xbfb8aa3b, v110
	v_mul_f32_e32 v119, 0xbfb8aa3b, v111
	v_exp_f32_e32 v118, v118
	v_exp_f32_e32 v119, v119
	v_add_f32_e32 v116, 1.0, v122
	v_add_f32_e32 v117, 1.0, v117
	v_rcp_f32_e32 v116, v116
	v_rcp_f32_e32 v117, v117
	v_add_f32_e32 v118, 1.0, v118
	v_add_f32_e32 v119, 1.0, v119
	v_rcp_f32_e32 v118, v118
	v_rcp_f32_e32 v119, v119
	v_pk_mul_f32 v[100:101], v[100:101], v[176:177] op_sel_hi:[1,0]
	v_pk_mul_f32 v[108:109], v[108:109], v[116:117]
	v_pk_mul_f32 v[104:105], v[104:105], v[176:177] op_sel_hi:[1,0]
	v_pk_mul_f32 v[100:101], v[100:101], v[108:109]
	v_pk_mul_f32 v[108:109], v[110:111], v[118:119]
	v_mul_f32_e32 v110, 0xbfb8aa3b, v104
	v_exp_f32_e32 v110, v110
	v_pk_mul_f32 v[102:103], v[102:103], v[176:177] op_sel_hi:[1,0]
	v_pk_mul_f32 v[106:107], v[106:107], v[176:177] op_sel_hi:[1,0]
	v_pk_mul_f32 v[102:103], v[102:103], v[108:109]
	v_mul_f32_e32 v108, 0xbfb8aa3b, v105
	v_exp_f32_e32 v109, v108
	v_add_f32_e32 v108, 1.0, v110
	v_mul_f32_e32 v110, 0xbfb8aa3b, v106
	v_mul_f32_e32 v111, 0xbfb8aa3b, v107
	v_exp_f32_e32 v110, v110
	v_exp_f32_e32 v111, v111
	v_add_f32_e32 v109, 1.0, v109
	v_rcp_f32_e32 v108, v108
	v_rcp_f32_e32 v109, v109
	v_add_f32_e32 v110, 1.0, v110
	v_add_f32_e32 v111, 1.0, v111
	v_rcp_f32_e32 v110, v110
	v_rcp_f32_e32 v111, v111
	v_pk_mul_f32 v[96:97], v[96:97], v[176:177] op_sel_hi:[1,0]
	v_pk_mul_f32 v[104:105], v[104:105], v[108:109]
	v_pk_mul_f32 v[92:93], v[92:93], v[174:175] op_sel_hi:[1,0]
	v_pk_mul_f32 v[104:105], v[96:97], v[104:105]
	v_pk_mul_f32 v[96:97], v[98:99], v[176:177] op_sel_hi:[1,0]
	v_pk_mul_f32 v[98:99], v[106:107], v[110:111]
	v_pk_mul_f32 v[94:95], v[94:95], v[174:175] op_sel_hi:[1,0]
	v_pk_mul_f32 v[106:107], v[96:97], v[98:99]
	v_cvt_pk_bf16_f32 v96, v100, v101
	v_mad_i64_i32 v[100:101], s[0:1], v164, s59, v[112:113]
	v_cvt_pk_bf16_f32 v97, v102, v103
	v_cvt_pk_bf16_f32 v98, v104, v105
	v_cvt_pk_bf16_f32 v99, v106, v107
	v_lshl_add_u64 v[100:101], v[100:101], 0, v[114:115]
	v_mul_f32_e32 v102, 0xbfb8aa3b, v92
	global_store_dwordx4 v[100:101], v[96:99], off
	v_exp_f32_e32 v102, v102
	v_pk_mul_f32 v[84:85], v[84:85], v[174:175] op_sel_hi:[1,0]
	v_mul_f32_e32 v96, 0xbfb8aa3b, v93
	v_exp_f32_e32 v97, v96
	v_mul_f32_e32 v98, 0xbfb8aa3b, v94
	v_mul_f32_e32 v99, 0xbfb8aa3b, v95
	v_exp_f32_e32 v98, v98
	v_exp_f32_e32 v99, v99
	v_add_f32_e32 v96, 1.0, v102
	v_add_f32_e32 v97, 1.0, v97
	v_rcp_f32_e32 v96, v96
	v_rcp_f32_e32 v97, v97
	v_add_f32_e32 v98, 1.0, v98
	v_add_f32_e32 v99, 1.0, v99
	v_rcp_f32_e32 v98, v98
	v_rcp_f32_e32 v99, v99
	v_pk_mul_f32 v[92:93], v[92:93], v[96:97]
	v_pk_mul_f32 v[88:89], v[88:89], v[174:175] op_sel_hi:[1,0]
	v_pk_mul_f32 v[84:85], v[84:85], v[92:93]
	v_pk_mul_f32 v[92:93], v[94:95], v[98:99]
	v_mul_f32_e32 v94, 0xbfb8aa3b, v88
	v_exp_f32_e32 v94, v94
	v_pk_mul_f32 v[86:87], v[86:87], v[174:175] op_sel_hi:[1,0]
	v_pk_mul_f32 v[90:91], v[90:91], v[174:175] op_sel_hi:[1,0]
	v_pk_mul_f32 v[86:87], v[86:87], v[92:93]
	v_mul_f32_e32 v92, 0xbfb8aa3b, v89
	v_exp_f32_e32 v93, v92
	v_add_f32_e32 v92, 1.0, v94
	v_mul_f32_e32 v94, 0xbfb8aa3b, v90
	v_mul_f32_e32 v95, 0xbfb8aa3b, v91
	v_exp_f32_e32 v94, v94
	v_exp_f32_e32 v95, v95
	v_add_f32_e32 v93, 1.0, v93
	v_rcp_f32_e32 v92, v92
	v_rcp_f32_e32 v93, v93
	v_add_f32_e32 v94, 1.0, v94
	v_add_f32_e32 v95, 1.0, v95
	v_rcp_f32_e32 v94, v94
	v_rcp_f32_e32 v95, v95
	v_pk_mul_f32 v[80:81], v[80:81], v[174:175] op_sel_hi:[1,0]
	v_pk_mul_f32 v[88:89], v[88:89], v[92:93]
	v_pk_mul_f32 v[76:77], v[76:77], v[170:171] op_sel_hi:[1,0]
	v_pk_mul_f32 v[88:89], v[80:81], v[88:89]
	v_pk_mul_f32 v[80:81], v[82:83], v[174:175] op_sel_hi:[1,0]
	v_pk_mul_f32 v[82:83], v[90:91], v[94:95]
	v_pk_mul_f32 v[78:79], v[78:79], v[170:171] op_sel_hi:[1,0]
	v_pk_mul_f32 v[90:91], v[80:81], v[82:83]
	v_cvt_pk_bf16_f32 v80, v84, v85
	v_mad_i64_i32 v[84:85], s[0:1], v160, s59, v[112:113]
	v_cvt_pk_bf16_f32 v81, v86, v87
	v_cvt_pk_bf16_f32 v82, v88, v89
	v_cvt_pk_bf16_f32 v83, v90, v91
	v_lshl_add_u64 v[84:85], v[84:85], 0, v[114:115]
	v_mul_f32_e32 v86, 0xbfb8aa3b, v76
	global_store_dwordx4 v[84:85], v[80:83], off
	v_exp_f32_e32 v86, v86
	v_pk_mul_f32 v[68:69], v[68:69], v[170:171] op_sel_hi:[1,0]
	v_mul_f32_e32 v80, 0xbfb8aa3b, v77
	v_exp_f32_e32 v81, v80
	v_mul_f32_e32 v82, 0xbfb8aa3b, v78
	v_mul_f32_e32 v83, 0xbfb8aa3b, v79
	v_exp_f32_e32 v82, v82
	v_exp_f32_e32 v83, v83
	v_add_f32_e32 v80, 1.0, v86
	v_add_f32_e32 v81, 1.0, v81
	v_rcp_f32_e32 v80, v80
	v_rcp_f32_e32 v81, v81
	v_add_f32_e32 v82, 1.0, v82
	v_add_f32_e32 v83, 1.0, v83
	v_rcp_f32_e32 v82, v82
	v_rcp_f32_e32 v83, v83
	v_pk_mul_f32 v[76:77], v[76:77], v[80:81]
	v_pk_mul_f32 v[72:73], v[72:73], v[170:171] op_sel_hi:[1,0]
	v_pk_mul_f32 v[68:69], v[68:69], v[76:77]
	v_pk_mul_f32 v[76:77], v[78:79], v[82:83]
	v_mul_f32_e32 v78, 0xbfb8aa3b, v72
	v_exp_f32_e32 v78, v78
	v_pk_mul_f32 v[70:71], v[70:71], v[170:171] op_sel_hi:[1,0]
	v_pk_mul_f32 v[74:75], v[74:75], v[170:171] op_sel_hi:[1,0]
	v_pk_mul_f32 v[70:71], v[70:71], v[76:77]
	v_mul_f32_e32 v76, 0xbfb8aa3b, v73
	v_exp_f32_e32 v77, v76
	v_add_f32_e32 v76, 1.0, v78
	v_mul_f32_e32 v78, 0xbfb8aa3b, v74
	v_mul_f32_e32 v79, 0xbfb8aa3b, v75
	v_exp_f32_e32 v78, v78
	v_exp_f32_e32 v79, v79
	v_add_f32_e32 v77, 1.0, v77
	v_rcp_f32_e32 v76, v76
	v_rcp_f32_e32 v77, v77
	v_add_f32_e32 v78, 1.0, v78
	v_add_f32_e32 v79, 1.0, v79
	v_rcp_f32_e32 v78, v78
	v_rcp_f32_e32 v79, v79
	v_pk_mul_f32 v[64:65], v[64:65], v[170:171] op_sel_hi:[1,0]
	v_pk_mul_f32 v[72:73], v[72:73], v[76:77]
	v_pk_mul_f32 v[60:61], v[60:61], v[166:167] op_sel_hi:[1,0]
	v_pk_mul_f32 v[72:73], v[64:65], v[72:73]
	v_pk_mul_f32 v[64:65], v[66:67], v[170:171] op_sel_hi:[1,0]
	v_pk_mul_f32 v[66:67], v[74:75], v[78:79]
	v_pk_mul_f32 v[62:63], v[62:63], v[166:167] op_sel_hi:[1,0]
	v_pk_mul_f32 v[74:75], v[64:65], v[66:67]
	v_cvt_pk_bf16_f32 v64, v68, v69
	v_mad_i64_i32 v[68:69], s[0:1], v156, s59, v[112:113]
	v_cvt_pk_bf16_f32 v65, v70, v71
	v_cvt_pk_bf16_f32 v66, v72, v73
	v_cvt_pk_bf16_f32 v67, v74, v75
	v_lshl_add_u64 v[68:69], v[68:69], 0, v[114:115]
	v_mul_f32_e32 v70, 0xbfb8aa3b, v60
	global_store_dwordx4 v[68:69], v[64:67], off
	v_exp_f32_e32 v70, v70
	v_pk_mul_f32 v[52:53], v[52:53], v[166:167] op_sel_hi:[1,0]
	v_mul_f32_e32 v64, 0xbfb8aa3b, v61
	v_exp_f32_e32 v65, v64
	v_mul_f32_e32 v66, 0xbfb8aa3b, v62
	v_mul_f32_e32 v67, 0xbfb8aa3b, v63
	v_exp_f32_e32 v66, v66
	v_exp_f32_e32 v67, v67
	v_add_f32_e32 v64, 1.0, v70
	v_add_f32_e32 v65, 1.0, v65
	v_rcp_f32_e32 v64, v64
	v_rcp_f32_e32 v65, v65
	v_add_f32_e32 v66, 1.0, v66
	v_add_f32_e32 v67, 1.0, v67
	v_rcp_f32_e32 v66, v66
	v_rcp_f32_e32 v67, v67
	v_pk_mul_f32 v[60:61], v[60:61], v[64:65]
	v_pk_mul_f32 v[56:57], v[56:57], v[166:167] op_sel_hi:[1,0]
	v_pk_mul_f32 v[52:53], v[52:53], v[60:61]
	v_pk_mul_f32 v[60:61], v[62:63], v[66:67]
	v_mul_f32_e32 v62, 0xbfb8aa3b, v56
	v_exp_f32_e32 v62, v62
	v_pk_mul_f32 v[54:55], v[54:55], v[166:167] op_sel_hi:[1,0]
	v_pk_mul_f32 v[58:59], v[58:59], v[166:167] op_sel_hi:[1,0]
	v_pk_mul_f32 v[54:55], v[54:55], v[60:61]
	v_mul_f32_e32 v60, 0xbfb8aa3b, v57
	v_exp_f32_e32 v61, v60
	v_add_f32_e32 v60, 1.0, v62
	v_mul_f32_e32 v62, 0xbfb8aa3b, v58
	v_mul_f32_e32 v63, 0xbfb8aa3b, v59
	v_exp_f32_e32 v62, v62
	v_exp_f32_e32 v63, v63
	v_add_f32_e32 v61, 1.0, v61
	v_rcp_f32_e32 v60, v60
	v_rcp_f32_e32 v61, v61
	v_add_f32_e32 v62, 1.0, v62
	v_add_f32_e32 v63, 1.0, v63
	v_rcp_f32_e32 v62, v62
	v_rcp_f32_e32 v63, v63
	v_pk_mul_f32 v[48:49], v[48:49], v[166:167] op_sel_hi:[1,0]
	v_pk_mul_f32 v[56:57], v[56:57], v[60:61]
	v_pk_mul_f32 v[44:45], v[44:45], v[162:163] op_sel_hi:[1,0]
	v_pk_mul_f32 v[56:57], v[48:49], v[56:57]
	v_pk_mul_f32 v[48:49], v[50:51], v[166:167] op_sel_hi:[1,0]
	v_pk_mul_f32 v[50:51], v[58:59], v[62:63]
	v_pk_mul_f32 v[46:47], v[46:47], v[162:163] op_sel_hi:[1,0]
	v_pk_mul_f32 v[58:59], v[48:49], v[50:51]
	v_cvt_pk_bf16_f32 v48, v52, v53
	v_mad_i64_i32 v[52:53], s[0:1], v152, s59, v[112:113]
	v_cvt_pk_bf16_f32 v49, v54, v55
	v_cvt_pk_bf16_f32 v50, v56, v57
	v_cvt_pk_bf16_f32 v51, v58, v59
	v_lshl_add_u64 v[52:53], v[52:53], 0, v[114:115]
	v_mul_f32_e32 v54, 0xbfb8aa3b, v44
	global_store_dwordx4 v[52:53], v[48:51], off
	v_exp_f32_e32 v54, v54
	v_pk_mul_f32 v[36:37], v[36:37], v[162:163] op_sel_hi:[1,0]
	v_mul_f32_e32 v48, 0xbfb8aa3b, v45
	v_exp_f32_e32 v49, v48
	v_mul_f32_e32 v50, 0xbfb8aa3b, v46
	v_mul_f32_e32 v51, 0xbfb8aa3b, v47
	v_exp_f32_e32 v50, v50
	v_exp_f32_e32 v51, v51
	v_add_f32_e32 v48, 1.0, v54
	v_add_f32_e32 v49, 1.0, v49
	v_rcp_f32_e32 v48, v48
	v_rcp_f32_e32 v49, v49
	v_add_f32_e32 v50, 1.0, v50
	v_add_f32_e32 v51, 1.0, v51
	v_rcp_f32_e32 v50, v50
	v_rcp_f32_e32 v51, v51
	v_pk_mul_f32 v[44:45], v[44:45], v[48:49]
	v_pk_mul_f32 v[40:41], v[40:41], v[162:163] op_sel_hi:[1,0]
	v_pk_mul_f32 v[36:37], v[36:37], v[44:45]
	v_pk_mul_f32 v[44:45], v[46:47], v[50:51]
	v_mul_f32_e32 v46, 0xbfb8aa3b, v40
	v_exp_f32_e32 v46, v46
	v_pk_mul_f32 v[38:39], v[38:39], v[162:163] op_sel_hi:[1,0]
	v_pk_mul_f32 v[42:43], v[42:43], v[162:163] op_sel_hi:[1,0]
	v_pk_mul_f32 v[38:39], v[38:39], v[44:45]
	v_mul_f32_e32 v44, 0xbfb8aa3b, v41
	v_exp_f32_e32 v45, v44
	v_add_f32_e32 v44, 1.0, v46
	v_mul_f32_e32 v46, 0xbfb8aa3b, v42
	v_mul_f32_e32 v47, 0xbfb8aa3b, v43
	v_exp_f32_e32 v46, v46
	v_exp_f32_e32 v47, v47
	v_add_f32_e32 v45, 1.0, v45
	v_rcp_f32_e32 v44, v44
	v_rcp_f32_e32 v45, v45
	v_add_f32_e32 v46, 1.0, v46
	v_add_f32_e32 v47, 1.0, v47
	v_rcp_f32_e32 v46, v46
	v_rcp_f32_e32 v47, v47
	v_pk_mul_f32 v[32:33], v[32:33], v[162:163] op_sel_hi:[1,0]
	v_pk_mul_f32 v[40:41], v[40:41], v[44:45]
	v_pk_mul_f32 v[28:29], v[28:29], v[158:159] op_sel_hi:[1,0]
	v_pk_mul_f32 v[40:41], v[32:33], v[40:41]
	v_pk_mul_f32 v[32:33], v[34:35], v[162:163] op_sel_hi:[1,0]
	v_pk_mul_f32 v[34:35], v[42:43], v[46:47]
	v_pk_mul_f32 v[30:31], v[30:31], v[158:159] op_sel_hi:[1,0]
	v_pk_mul_f32 v[42:43], v[32:33], v[34:35]
	v_cvt_pk_bf16_f32 v32, v36, v37
	v_mad_i64_i32 v[36:37], s[0:1], v150, s59, v[112:113]
	v_cvt_pk_bf16_f32 v33, v38, v39
	v_cvt_pk_bf16_f32 v34, v40, v41
	v_cvt_pk_bf16_f32 v35, v42, v43
	v_lshl_add_u64 v[36:37], v[36:37], 0, v[114:115]
	v_mul_f32_e32 v38, 0xbfb8aa3b, v28
	global_store_dwordx4 v[36:37], v[32:35], off
	v_exp_f32_e32 v38, v38
	v_pk_mul_f32 v[20:21], v[20:21], v[158:159] op_sel_hi:[1,0]
	v_mul_f32_e32 v32, 0xbfb8aa3b, v29
	v_exp_f32_e32 v33, v32
	v_mul_f32_e32 v34, 0xbfb8aa3b, v30
	v_mul_f32_e32 v35, 0xbfb8aa3b, v31
	v_exp_f32_e32 v34, v34
	v_exp_f32_e32 v35, v35
	v_add_f32_e32 v32, 1.0, v38
	v_add_f32_e32 v33, 1.0, v33
	v_rcp_f32_e32 v32, v32
	v_rcp_f32_e32 v33, v33
	v_add_f32_e32 v34, 1.0, v34
	v_add_f32_e32 v35, 1.0, v35
	v_rcp_f32_e32 v34, v34
	v_rcp_f32_e32 v35, v35
	v_pk_mul_f32 v[28:29], v[28:29], v[32:33]
	v_pk_mul_f32 v[24:25], v[24:25], v[158:159] op_sel_hi:[1,0]
	v_pk_mul_f32 v[20:21], v[20:21], v[28:29]
	v_pk_mul_f32 v[28:29], v[30:31], v[34:35]
	v_mul_f32_e32 v30, 0xbfb8aa3b, v24
	v_exp_f32_e32 v30, v30
	v_pk_mul_f32 v[22:23], v[22:23], v[158:159] op_sel_hi:[1,0]
	v_pk_mul_f32 v[26:27], v[26:27], v[158:159] op_sel_hi:[1,0]
	v_pk_mul_f32 v[22:23], v[22:23], v[28:29]
	v_mul_f32_e32 v28, 0xbfb8aa3b, v25
	v_exp_f32_e32 v29, v28
	v_add_f32_e32 v28, 1.0, v30
	v_mul_f32_e32 v30, 0xbfb8aa3b, v26
	v_mul_f32_e32 v31, 0xbfb8aa3b, v27
	v_exp_f32_e32 v30, v30
	v_exp_f32_e32 v31, v31
	v_add_f32_e32 v29, 1.0, v29
	v_rcp_f32_e32 v28, v28
	v_rcp_f32_e32 v29, v29
	v_add_f32_e32 v30, 1.0, v30
	v_add_f32_e32 v31, 1.0, v31
	v_rcp_f32_e32 v30, v30
	v_rcp_f32_e32 v31, v31
	v_pk_mul_f32 v[16:17], v[16:17], v[158:159] op_sel_hi:[1,0]
	v_pk_mul_f32 v[24:25], v[24:25], v[28:29]
	v_pk_mul_f32 v[12:13], v[12:13], v[154:155] op_sel_hi:[1,0]
	v_pk_mul_f32 v[24:25], v[16:17], v[24:25]
	v_pk_mul_f32 v[16:17], v[18:19], v[158:159] op_sel_hi:[1,0]
	v_pk_mul_f32 v[18:19], v[26:27], v[30:31]
	v_pk_mul_f32 v[14:15], v[14:15], v[154:155] op_sel_hi:[1,0]
	v_pk_mul_f32 v[26:27], v[16:17], v[18:19]
	v_cvt_pk_bf16_f32 v16, v20, v21
	v_mad_i64_i32 v[20:21], s[0:1], v148, s59, v[112:113]
	v_cvt_pk_bf16_f32 v17, v22, v23
	v_cvt_pk_bf16_f32 v18, v24, v25
	v_cvt_pk_bf16_f32 v19, v26, v27
	v_lshl_add_u64 v[20:21], v[20:21], 0, v[114:115]
	v_mul_f32_e32 v22, 0xbfb8aa3b, v12
	global_store_dwordx4 v[20:21], v[16:19], off
	v_exp_f32_e32 v22, v22
	v_pk_mul_f32 v[4:5], v[4:5], v[154:155] op_sel_hi:[1,0]
	v_mul_f32_e32 v16, 0xbfb8aa3b, v13
	v_exp_f32_e32 v17, v16
	v_mul_f32_e32 v18, 0xbfb8aa3b, v14
	v_mul_f32_e32 v19, 0xbfb8aa3b, v15
	v_exp_f32_e32 v18, v18
	v_exp_f32_e32 v19, v19
	v_add_f32_e32 v16, 1.0, v22
	v_add_f32_e32 v17, 1.0, v17
	v_rcp_f32_e32 v16, v16
	v_rcp_f32_e32 v17, v17
	v_add_f32_e32 v18, 1.0, v18
	v_add_f32_e32 v19, 1.0, v19
	v_rcp_f32_e32 v18, v18
	v_rcp_f32_e32 v19, v19
	v_pk_mul_f32 v[12:13], v[12:13], v[16:17]
	v_pk_mul_f32 v[8:9], v[8:9], v[154:155] op_sel_hi:[1,0]
	v_pk_mul_f32 v[4:5], v[4:5], v[12:13]
	v_pk_mul_f32 v[12:13], v[14:15], v[18:19]
	v_mul_f32_e32 v14, 0xbfb8aa3b, v8
	v_exp_f32_e32 v14, v14
	v_pk_mul_f32 v[6:7], v[6:7], v[154:155] op_sel_hi:[1,0]
	v_pk_mul_f32 v[10:11], v[10:11], v[154:155] op_sel_hi:[1,0]
	v_pk_mul_f32 v[6:7], v[6:7], v[12:13]
	v_mul_f32_e32 v12, 0xbfb8aa3b, v9
	v_exp_f32_e32 v13, v12
	v_add_f32_e32 v12, 1.0, v14
	v_mul_f32_e32 v14, 0xbfb8aa3b, v10
	v_mul_f32_e32 v15, 0xbfb8aa3b, v11
	v_exp_f32_e32 v14, v14
	v_exp_f32_e32 v15, v15
	v_add_f32_e32 v13, 1.0, v13
	v_rcp_f32_e32 v12, v12
	v_rcp_f32_e32 v13, v13
	v_add_f32_e32 v14, 1.0, v14
	v_add_f32_e32 v15, 1.0, v15
	v_rcp_f32_e32 v14, v14
	v_rcp_f32_e32 v15, v15
	v_pk_mul_f32 v[0:1], v[0:1], v[154:155] op_sel_hi:[1,0]
	v_pk_mul_f32 v[8:9], v[8:9], v[12:13]
	s_and_b64 vcc, exec, s[2:3]
	v_pk_mul_f32 v[8:9], v[0:1], v[8:9]
	v_pk_mul_f32 v[0:1], v[2:3], v[154:155] op_sel_hi:[1,0]
	v_pk_mul_f32 v[2:3], v[10:11], v[14:15]
	s_mov_b32 s5, s12
	v_pk_mul_f32 v[10:11], v[0:1], v[2:3]
	v_cvt_pk_bf16_f32 v0, v4, v5
	v_mad_i64_i32 v[4:5], s[0:1], v146, s59, v[112:113]
	v_cvt_pk_bf16_f32 v1, v6, v7
	v_cvt_pk_bf16_f32 v2, v8, v9
	v_cvt_pk_bf16_f32 v3, v10, v11
	v_lshl_add_u64 v[4:5], v[4:5], 0, v[114:115]
	s_mov_b32 s4, s36
	s_mov_b64 s[42:43], s[40:41]
	s_mov_b64 s[44:45], s[38:39]
	global_store_dwordx4 v[4:5], v[0:3], off
	s_waitcnt vmcnt(8)
	v_xor_b32_e32 v184, 16, v177
	v_xor_b32_e32 v185, 32, v177
	v_lshlrev_b32_e32 v184, 2, v184
	v_lshlrev_b32_e32 v185, 2, v185
	v_mov_b32_e32 v190, s10
	v_pk_add_f32 v[216:217], v[216:217], v[218:219]
	v_pk_add_f32 v[220:221], v[220:221], v[222:223]
	v_pk_add_f32 v[224:225], v[224:225], v[226:227]
	v_pk_add_f32 v[196:197], v[196:197], v[198:199]
	v_pk_add_f32 v[200:201], v[200:201], v[202:203]
	v_pk_add_f32 v[204:205], v[204:205], v[206:207]
	v_pk_add_f32 v[208:209], v[208:209], v[210:211]
	v_pk_add_f32 v[212:213], v[212:213], v[214:215]
	v_add_f32_e32 v216, v216, v217
	v_add_f32_e32 v220, v220, v221
	v_add_f32_e32 v224, v224, v225
	v_add_f32_e32 v196, v196, v197
	v_add_f32_e32 v200, v200, v201
	v_add_f32_e32 v204, v204, v205
	v_add_f32_e32 v208, v208, v209
	v_add_f32_e32 v212, v212, v213
	ds_bpermute_b32 v218, v184, v216
	ds_bpermute_b32 v219, v184, v220
	ds_bpermute_b32 v222, v184, v224
	ds_bpermute_b32 v223, v184, v196
	ds_bpermute_b32 v226, v184, v200
	ds_bpermute_b32 v227, v184, v204
	ds_bpermute_b32 v198, v184, v208
	ds_bpermute_b32 v199, v184, v212
	s_waitcnt lgkmcnt(0)
	v_add_f32_e32 v216, v216, v218
	v_add_f32_e32 v220, v220, v219
	v_add_f32_e32 v224, v224, v222
	v_add_f32_e32 v196, v196, v223
	v_add_f32_e32 v200, v200, v226
	v_add_f32_e32 v204, v204, v227
	v_add_f32_e32 v208, v208, v198
	v_add_f32_e32 v212, v212, v199
	ds_bpermute_b32 v218, v185, v216
	ds_bpermute_b32 v219, v185, v220
	ds_bpermute_b32 v222, v185, v224
	ds_bpermute_b32 v223, v185, v196
	ds_bpermute_b32 v226, v185, v200
	ds_bpermute_b32 v227, v185, v204
	ds_bpermute_b32 v198, v185, v208
	ds_bpermute_b32 v199, v185, v212
	s_waitcnt lgkmcnt(0)
	v_add_f32_e32 v216, v216, v218
	v_add_f32_e32 v220, v220, v219
	v_add_f32_e32 v224, v224, v222
	v_add_f32_e32 v196, v196, v223
	v_add_f32_e32 v200, v200, v226
	v_add_f32_e32 v204, v204, v227
	v_add_f32_e32 v208, v208, v198
	v_add_f32_e32 v212, v212, v199
	v_fma_f32 v216, v216, s8, v190
	v_fma_f32 v220, v220, s8, v190
	v_fma_f32 v224, v224, s8, v190
	v_fma_f32 v196, v196, s8, v190
	v_fma_f32 v200, v200, s8, v190
	v_fma_f32 v204, v204, s8, v190
	v_fma_f32 v208, v208, s8, v190
	v_fma_f32 v212, v212, s8, v190
	v_rsq_f32_e32 v240, v216
	v_rsq_f32_e32 v176, v220
	v_rsq_f32_e32 v174, v224
	v_rsq_f32_e32 v170, v196
	v_rsq_f32_e32 v166, v200
	v_rsq_f32_e32 v162, v204
	v_rsq_f32_e32 v158, v208
	v_rsq_f32_e32 v241, v212
	s_and_b64 vcc, exec, s[2:3]
	s_mov_b32 s5, s12
	s_mov_b32 s4, s36
	s_cbranch_vccz .LBB0_1090
	s_waitcnt vmcnt(0)
	s_cmpk_gt_u32 s9, 0xff
	s_cbranch_scc1 .LBB0_1097
	s_barrier
